# sample-group pool items moved out of P2 into the shadow of grid barrier 2 (wave 1 of blocks 0..127 runs them while thread 0 runs the barrier protocol)
# speedup vs baseline: 1.0037x; 1.0037x over previous
; #define GAS __attribute__((address_space(1)))
; __device__ __forceinline__ void pool_phase(Frame& F) {
;     const int total = (MT / 8) * 64;
;     for (int i = blockIdx.x * 512 + F.tid; i < total; i += F.G * 512) {
;         const int r0 = (i >> 6) * 8, c = (i & 63) * 4, g = c >> 6; const bool smp = r0 >= TP; const int rr = smp ? r0 - TP : r0; const int b = smp ? rr >> 3 : rr >> 11, t0 = smp ? 0 : rr & 2047;
;         const bf16* ub = F.U + (size_t)(r0 - t0) * 256 + c;
;         f32x4 x[23];
; #pragma unroll
;         for (int k = 0; k < 23; ++k) { const int tau = t0 - 15 + k;
;             if (tau >= 0) { const u32x2v hb = *(const GAS u32x2v*)(ub + (size_t)tau * 256);
;                 x[k] = (f32x4){__builtin_bit_cast(float, hb.x << 16), __builtin_bit_cast(float, hb.x & 0xffff0000u), __builtin_bit_cast(float, hb.y << 16), __builtin_bit_cast(float, hb.y & 0xffff0000u)}; } else if (smp) x[k] = *(const GAS f32x4*)(F.state_pool + ((size_t)b * 15 + 15 + tau) * 256 + c); else x[k] = (f32x4){0.f, 0.f, 0.f, 0.f}; }
.LBB0_390:
	s_cmp_lt_i32 s70, 3
	s_cselect_b64 s[2:3], -1, 0
	s_add_u32 s38, s68, 0x5300000
	s_addc_u32 s39, s69, 0
	s_and_b64 s[6:7], s[2:3], s[0:1]
	s_andn2_b64 vcc, exec, s[6:7]
	s_cbranch_vccnz .LBB0_579
	s_mov_b32 s29, 0
.Lpool_shadow_entry:
	s_mov_b32 s28, s88
	v_readfirstlane_b32 s40, v0
	v_readlane_b32 s48, v254, 9
	v_readlane_b32 s49, v254, 10
	v_readlane_b32 s50, v254, 58
	v_readlane_b32 s51, v254, 59
	s_nop 4
	s_lshr_b32 s40, s40, 6
	s_lshl_b32 s41, s88, 3
	s_add_i32 s40, s40, s41
	s_lshl_b32 s41, s79, 3
	s_add_u32 s44, s68, 0x7500000
	s_addc_u32 s45, s69, 0
	s_sub_u32 s44, s44, 0x1e00
	s_subb_u32 s45, s45, 0
	s_add_u32 s46, s68, 0x5300000
	s_addc_u32 s47, s69, 0
	s_mov_b32 s54, 0xffff0000
	s_mov_b32 s55, -1
	s_mov_b32 s56, 0
	s_mov_b32 s57, -1
	s_mov_b32 s58, 0
	s_mov_b32 s59, 0xffff0000
	v_lshlrev_b32_e32 v244, 3, v202
	v_lshlrev_b32_e32 v245, 4, v202
	v_lshrrev_b32_e32 v247, 4, v202
	v_lshlrev_b32_e64 v246, v247, 2
	v_cvt_f32_u32_e32 v246, v246
.Lpool_loop:
	s_cmp_lg_u32 s29, 0
	s_cbranch_scc1 .Lpool_shadow_go
	s_cmp_ge_u32 s40, 0x800
	s_cbranch_scc1 .Lpool_prompt_done
	s_lshl_b32 s42, s40, 3
	s_and_b32 s43, s40, 0xff
	s_lshl_b32 s43, s43, 3
	s_lshl_b32 s32, s42, 9
	s_add_u32 s60, s44, s32
	s_addc_u32 s61, s45, 0
	s_add_u32 s62, s60, 0x1000
	s_addc_u32 s63, s61, 0
	s_add_u32 s30, s60, 0x2000
	s_addc_u32 s31, s61, 0
	global_load_dwordx2 v[6:7], v244, s[60:61]
	global_load_dwordx2 v[10:11], v244, s[60:61] offset:512
	global_load_dwordx2 v[14:15], v244, s[60:61] offset:1024
	global_load_dwordx2 v[18:19], v244, s[60:61] offset:1536
	global_load_dwordx2 v[22:23], v244, s[60:61] offset:2048
	global_load_dwordx2 v[26:27], v244, s[60:61] offset:2560
	global_load_dwordx2 v[30:31], v244, s[60:61] offset:3072
	global_load_dwordx2 v[34:35], v244, s[60:61] offset:3584
	global_load_dwordx2 v[38:39], v244, s[62:63]
	global_load_dwordx2 v[42:43], v244, s[62:63] offset:512
	global_load_dwordx2 v[46:47], v244, s[62:63] offset:1024
	global_load_dwordx2 v[50:51], v244, s[62:63] offset:1536
	global_load_dwordx2 v[54:55], v244, s[62:63] offset:2048
	global_load_dwordx2 v[58:59], v244, s[62:63] offset:2560
	global_load_dwordx2 v[62:63], v244, s[62:63] offset:3072
	global_load_dwordx2 v[66:67], v244, s[62:63] offset:3584
	global_load_dwordx2 v[70:71], v244, s[30:31]
	global_load_dwordx2 v[74:75], v244, s[30:31] offset:512
	global_load_dwordx2 v[78:79], v244, s[30:31] offset:1024
	global_load_dwordx2 v[82:83], v244, s[30:31] offset:1536
	global_load_dwordx2 v[86:87], v244, s[30:31] offset:2048
	global_load_dwordx2 v[90:91], v244, s[30:31] offset:2560
	global_load_dwordx2 v[94:95], v244, s[30:31] offset:3072
	s_waitcnt vmcnt(0)
	v_lshlrev_b32_e32 v4, 16, v6
	v_and_b32_e32 v5, s59, v6
	v_lshlrev_b32_e32 v6, 16, v7
	v_and_b32_e32 v7, s59, v7
	v_lshlrev_b32_e32 v8, 16, v10
	v_and_b32_e32 v9, s59, v10
	v_lshlrev_b32_e32 v10, 16, v11
	v_and_b32_e32 v11, s59, v11
	v_lshlrev_b32_e32 v12, 16, v14
	v_and_b32_e32 v13, s59, v14
	v_lshlrev_b32_e32 v14, 16, v15
	v_and_b32_e32 v15, s59, v15
	v_lshlrev_b32_e32 v16, 16, v18
	v_and_b32_e32 v17, s59, v18
	v_lshlrev_b32_e32 v18, 16, v19
	v_and_b32_e32 v19, s59, v19
	v_lshlrev_b32_e32 v20, 16, v22
	v_and_b32_e32 v21, s59, v22
	v_lshlrev_b32_e32 v22, 16, v23
	v_and_b32_e32 v23, s59, v23
	v_lshlrev_b32_e32 v24, 16, v26
	v_and_b32_e32 v25, s59, v26
	v_lshlrev_b32_e32 v26, 16, v27
	v_and_b32_e32 v27, s59, v27
	v_lshlrev_b32_e32 v28, 16, v30
	v_and_b32_e32 v29, s59, v30
	v_lshlrev_b32_e32 v30, 16, v31
	v_and_b32_e32 v31, s59, v31
	v_lshlrev_b32_e32 v32, 16, v34
	v_and_b32_e32 v33, s59, v34
	v_lshlrev_b32_e32 v34, 16, v35
	v_and_b32_e32 v35, s59, v35
	v_lshlrev_b32_e32 v36, 16, v38
	v_and_b32_e32 v37, s59, v38
	v_lshlrev_b32_e32 v38, 16, v39
	v_and_b32_e32 v39, s59, v39
	v_lshlrev_b32_e32 v40, 16, v42
	v_and_b32_e32 v41, s59, v42
	v_lshlrev_b32_e32 v42, 16, v43
	v_and_b32_e32 v43, s59, v43
	v_lshlrev_b32_e32 v44, 16, v46
	v_and_b32_e32 v45, s59, v46
	v_lshlrev_b32_e32 v46, 16, v47
	v_and_b32_e32 v47, s59, v47
	v_lshlrev_b32_e32 v48, 16, v50
	v_and_b32_e32 v49, s59, v50
	v_lshlrev_b32_e32 v50, 16, v51
	v_and_b32_e32 v51, s59, v51
	v_lshlrev_b32_e32 v52, 16, v54
	v_and_b32_e32 v53, s59, v54
	v_lshlrev_b32_e32 v54, 16, v55
	v_and_b32_e32 v55, s59, v55
	v_lshlrev_b32_e32 v56, 16, v58
	v_and_b32_e32 v57, s59, v58
	v_lshlrev_b32_e32 v58, 16, v59
	v_and_b32_e32 v59, s59, v59
	v_lshlrev_b32_e32 v60, 16, v62
	v_and_b32_e32 v61, s59, v62
	v_lshlrev_b32_e32 v62, 16, v63
	v_and_b32_e32 v63, s59, v63
	s_cmp_ge_u32 s43, 16
	s_cbranch_scc1 .Lpool_common
	v_mov_b32_e32 v4, 0
	v_mov_b32_e32 v5, 0
	v_mov_b32_e32 v6, 0
	v_mov_b32_e32 v7, 0
	v_mov_b32_e32 v8, 0
	v_mov_b32_e32 v9, 0
	v_mov_b32_e32 v10, 0
	v_mov_b32_e32 v11, 0
	v_mov_b32_e32 v12, 0
	v_mov_b32_e32 v13, 0
	v_mov_b32_e32 v14, 0
	v_mov_b32_e32 v15, 0
	v_mov_b32_e32 v16, 0
	v_mov_b32_e32 v17, 0
	v_mov_b32_e32 v18, 0
	v_mov_b32_e32 v19, 0
	v_mov_b32_e32 v20, 0
	v_mov_b32_e32 v21, 0
	v_mov_b32_e32 v22, 0
	v_mov_b32_e32 v23, 0
	v_mov_b32_e32 v24, 0
	v_mov_b32_e32 v25, 0
	v_mov_b32_e32 v26, 0
	v_mov_b32_e32 v27, 0
	v_mov_b32_e32 v28, 0
	v_mov_b32_e32 v29, 0
	v_mov_b32_e32 v30, 0
	v_mov_b32_e32 v31, 0
	s_cmp_eq_u32 s43, 8
	s_cbranch_scc1 .Lpool_common
	v_mov_b32_e32 v32, 0
	v_mov_b32_e32 v33, 0
	v_mov_b32_e32 v34, 0
	v_mov_b32_e32 v35, 0
	v_mov_b32_e32 v36, 0
	v_mov_b32_e32 v37, 0
	v_mov_b32_e32 v38, 0
	v_mov_b32_e32 v39, 0
	v_mov_b32_e32 v40, 0
	v_mov_b32_e32 v41, 0
	v_mov_b32_e32 v42, 0
	v_mov_b32_e32 v43, 0
	v_mov_b32_e32 v44, 0
	v_mov_b32_e32 v45, 0
	v_mov_b32_e32 v46, 0
	v_mov_b32_e32 v47, 0
	v_mov_b32_e32 v48, 0
	v_mov_b32_e32 v49, 0
	v_mov_b32_e32 v50, 0
	v_mov_b32_e32 v51, 0
	v_mov_b32_e32 v52, 0
	v_mov_b32_e32 v53, 0
	v_mov_b32_e32 v54, 0
	v_mov_b32_e32 v55, 0
	v_mov_b32_e32 v56, 0
	v_mov_b32_e32 v57, 0
	v_mov_b32_e32 v58, 0
	v_mov_b32_e32 v59, 0
	v_mov_b32_e32 v60, 0
	v_mov_b32_e32 v61, 0
	v_mov_b32_e32 v62, 0
	v_mov_b32_e32 v63, 0
	s_branch .Lpool_common

; __device__ __forceinline__ void pool_phase(Frame& F) {
;     ...
;     for (int i = blockIdx.x * 512 + F.tid; i < total; i += F.G * 512) {
;         const int r0 = (i >> 6) * 8, c = (i & 63) * 4, g = c >> 6; const bool smp = r0 >= TP; const int rr = smp ? r0 - TP : r0; const int b = smp ? rr >> 3 : rr >> 11, t0 = smp ? 0 : rr & 2047;
;         const bf16* ub = F.U + (size_t)(r0 - t0) * 256 + c;
.Lpool_prompt_done:
	s_cmp_eq_u32 s29, 0
	s_cbranch_scc1 .Lpool_done
	v_readfirstlane_b32 s32, v0
	s_nop 3
	s_cmp_ge_u32 s32, 64
	s_cbranch_scc1 .Lpool_done
	s_add_i32 s40, s88, 0x800

; #define GAS __attribute__((address_space(1)))
; #define LAS __attribute__((address_space(3)))
; __device__ __forceinline__ void hgrn_passA(Frame& F, u32x2v* HU, float* HD) {
;     LAS unsigned char* KT = F.lds;
;     LAS unsigned char* VT = F.lds + 65536;
;     LAS float* segtot = (LAS float*)F.lds;
;     const int tid = F.tid, c8 = tid & 15, tq = tid >> 4, w = F.wave, lane = F.lane, l15 = lane & 15, lq = lane >> 4;
;     for (int u = blockIdx.x; u < HG_NU; u += F.G) {
;         const int sc = u & 7, bh = u >> 3, b = bh >> 2, h = bh & 3;
;         const size_t rbase = (size_t)(b * 2048 + sc * 256 + tq * 8) * 512 + h * 128 + 8 * c8;
;         f32x4 lf[8][2]; v4u vq[8];
; #pragma unroll
;         for (int i = 0; i < 8; ++i) { typedef _Float16 h8_t __attribute__((ext_vector_type(8))); const h8_t hv = *(const GAS h8_t*)(F.LOGF + rbase + (size_t)i * 512);
;             lf[i][0] = (f32x4){(float)hv[0], (float)hv[1], (float)hv[2], (float)hv[3]}; lf[i][1] = (f32x4){(float)hv[4], (float)hv[5], (float)hv[6], (float)hv[7]};
;             }
; #pragma unroll
;         for (int i = 1; i < 8; ++i) { lf[i][0] += lf[i - 1][0]; lf[i][1] += lf[i - 1][1]; }
;         *(LAS f32x4*)(segtot + tq * 128 + 8 * c8) = lf[7][0]; *(LAS f32x4*)(segtot + tq * 128 + 8 * c8 + 4) = lf[7][1];
;         __syncthreads();
;         f32x4 off[2] = {(f32x4){0.f, 0.f, 0.f, 0.f}, (f32x4){0.f, 0.f, 0.f, 0.f}}, aend[2] = {(f32x4){0.f, 0.f, 0.f, 0.f}, (f32x4){0.f, 0.f, 0.f, 0.f}};
; #pragma unroll 8
;         for (int s2 = 0; s2 < 32; ++s2) { const f32x4 t0 = *(const LAS f32x4*)(segtot + s2 * 128 + 8 * c8), t1 = *(const LAS f32x4*)(segtot + s2 * 128 + 8 * c8 + 4);
;             aend[0] += t0; aend[1] += t1; if (s2 < tq) { off[0] += t0; off[1] += t1; } }
;         __syncthreads();
;         if (tq == 0) { f32x4 d0, d1;
; #pragma unroll
;             for (int e = 0; e < 4; ++e) { d0[e] = __expf(aend[0][e]); d1[e] = __expf(aend[1][e]); }
;             *(GAS f32x4*)(HD + (size_t)u * 128 + 8 * c8) = d0; *(GAS f32x4*)(HD + (size_t)u * 128 + 8 * c8 + 4) = d1; }
; #pragma unroll
;         for (int jh = 0; jh < 2; ++jh) {
;             unsigned ke[4][4];
; #pragma unroll
;             for (int i = 0; i < 8; ++i)
; #pragma unroll
;                 for (int jj = 0; jj < 4; ++jj) { const int j = 4 * jh + jj; const float kk = 1.f - __expf(i > 0 ? lf[i][jh][jj] - lf[i - 1][jh][jj] : lf[i][jh][jj]);
.Lpool_shadow_go:
	s_add_i32 s40, s88, 0x800
	s_branch .Lpool_sloop
.Lpool_done:
	s_cmp_lg_u32 s29, 0
	s_cbranch_scc1 .Lpool_shadow_ret
	s_mov_b32 s88, s28
	s_cmpk_gt_i32 s28, 0xff
	s_cbranch_scc1 .LBB0_579
	v_lshlrev_b32_e32 v111, 3, v0
	s_waitcnt lgkmcnt(0)
	v_and_b32_e32 v54, 0x78, v111
	v_and_b32_e32 v110, 15, v0
	v_mov_b32_e32 v57, 0
	v_lshlrev_b32_e32 v56, 2, v54
	v_lshl_add_u64 v[2:3], s[68:69], 0, v[56:57]
	s_mov_b64 s[2:3], 0x5200000
	v_readlane_b32 s0, v254, 39
	v_or_b32_e32 v52, 0x70, v110
	v_lshl_add_u64 v[58:59], v[2:3], 0, s[2:3]
	v_lshl_or_b32 v2, s0, 4, v110
	v_lshlrev_b32_e32 v53, 9, v52
	v_lshrrev_b32_e32 v52, 3, v52
	v_lshrrev_b32_e32 v55, 4, v202
	v_add_u32_e32 v114, 0, v56
	v_lshrrev_b32_e32 v3, 3, v2
	v_lshlrev_b32_e32 v56, 3, v202
	v_bitop3_b32 v52, v52, v0, 15 bitop3:0x78
	v_xor_b32_e32 v4, v3, v0
	v_lshl_add_u32 v5, v2, 9, 0
	v_lshl_add_u64 v[2:3], s[68:69], 0, v[56:57]
	s_add_i32 s2, 0, 0x10000
	v_xor_b32_e32 v56, v52, v55
	v_bfe_u32 v31, v0, 3, 1
	v_or_b32_e32 v34, 16, v110
	v_lshl_add_u32 v62, v56, 4, s2
	v_or_b32_e32 v56, 4, v55
	v_bitop3_b32 v31, v31, v0, 15 bitop3:0x78
	v_lshlrev_b32_e32 v35, 9, v34
	v_lshrrev_b32_e32 v34, 3, v34
	v_or_b32_e32 v37, 32, v110
	v_bitop3_b32 v60, v4, v56, 15 bitop3:0x6c
	v_bitop3_b32 v34, v34, v0, 15 bitop3:0x78
	v_lshlrev_b32_e32 v38, 9, v37
	v_lshrrev_b32_e32 v37, 3, v37
	v_or_b32_e32 v40, 48, v110
	v_lshlrev_b32_e32 v63, 4, v60
	v_xor_b32_e32 v60, v31, v56
	v_bitop3_b32 v37, v37, v0, 15 bitop3:0x78
	v_lshlrev_b32_e32 v41, 9, v40
	v_lshrrev_b32_e32 v40, 3, v40
	v_or_b32_e32 v43, 64, v110
	v_lshl_add_u32 v64, v60, 4, s2
	v_xor_b32_e32 v60, v34, v56
	v_bitop3_b32 v40, v40, v0, 15 bitop3:0x78
	v_lshlrev_b32_e32 v44, 9, v43
	v_lshrrev_b32_e32 v43, 3, v43
	v_or_b32_e32 v46, 0x50, v110
	v_lshl_add_u32 v65, v60, 4, s2
	v_xor_b32_e32 v60, v37, v56
	v_bitop3_b32 v43, v43, v0, 15 bitop3:0x78
	v_lshlrev_b32_e32 v47, 9, v46
	v_lshrrev_b32_e32 v46, 3, v46
	v_or_b32_e32 v49, 0x60, v110
	v_lshl_add_u32 v66, v60, 4, s2
	v_xor_b32_e32 v60, v40, v56
	v_bitop3_b32 v46, v46, v0, 15 bitop3:0x78
	v_lshlrev_b32_e32 v50, 9, v49
	v_lshrrev_b32_e32 v49, 3, v49
	v_lshl_add_u32 v67, v60, 4, s2
	v_xor_b32_e32 v60, v43, v56
	v_bitop3_b32 v49, v49, v0, 15 bitop3:0x78
	v_lshl_add_u32 v68, v60, 4, s2
	v_xor_b32_e32 v60, v46, v56
	v_lshl_add_u32 v69, v60, 4, s2
	v_xor_b32_e32 v60, v49, v56
	v_xor_b32_e32 v56, v52, v56
	v_lshl_add_u32 v71, v56, 4, s2
	v_or_b32_e32 v56, 8, v55
	v_lshl_add_u32 v70, v60, 4, s2
	v_bitop3_b32 v60, v4, v56, 15 bitop3:0x6c
	v_lshlrev_b32_e32 v72, 4, v60
	v_xor_b32_e32 v60, v31, v56
	v_lshl_add_u32 v73, v60, 4, s2
	v_xor_b32_e32 v60, v34, v56
	v_lshl_add_u32 v74, v60, 4, s2
	v_xor_b32_e32 v60, v37, v56
	v_lshl_add_u32 v75, v60, 4, s2
	v_xor_b32_e32 v60, v40, v56
	v_lshl_add_u32 v76, v60, 4, s2
	v_xor_b32_e32 v60, v43, v56
	v_lshl_add_u32 v77, v60, 4, s2
	v_xor_b32_e32 v60, v46, v56
	v_lshl_add_u32 v78, v60, 4, s2
	v_xor_b32_e32 v60, v49, v56
	v_xor_b32_e32 v56, v52, v56
	v_lshl_add_u32 v80, v56, 4, s2
	v_or_b32_e32 v56, 12, v55
	v_lshl_add_u32 v79, v60, 4, s2
	v_bitop3_b32 v60, v4, v56, 15 bitop3:0x6c
	v_lshlrev_b32_e32 v81, 4, v60
	v_xor_b32_e32 v60, v31, v56
	v_lshl_add_u32 v82, v60, 4, s2
	v_xor_b32_e32 v60, v34, v56
	v_lshl_add_u32 v83, v60, 4, s2
	v_xor_b32_e32 v60, v37, v56
	v_lshl_add_u32 v84, v60, 4, s2
	v_xor_b32_e32 v60, v40, v56
	v_lshl_add_u32 v85, v60, 4, s2
	v_xor_b32_e32 v60, v43, v56
	v_lshl_add_u32 v86, v60, 4, s2
	v_xor_b32_e32 v60, v46, v56
	v_lshl_add_u32 v87, v60, 4, s2
	v_xor_b32_e32 v60, v49, v56
	v_xor_b32_e32 v56, v52, v56
	v_lshl_add_u32 v89, v56, 4, s2
	v_or_b32_e32 v56, 16, v55
	v_lshl_add_u32 v88, v60, 4, s2
	v_bitop3_b32 v60, v4, v56, 15 bitop3:0x6c
	v_lshlrev_b32_e32 v90, 4, v60
	v_xor_b32_e32 v60, v31, v56
	v_lshl_add_u32 v91, v60, 4, s2
	v_xor_b32_e32 v60, v34, v56
	v_lshl_add_u32 v92, v60, 4, s2
	v_xor_b32_e32 v60, v37, v56
	v_lshl_add_u32 v93, v60, 4, s2
	v_xor_b32_e32 v60, v40, v56
	v_lshl_add_u32 v94, v60, 4, s2
	v_xor_b32_e32 v60, v43, v56
	v_lshl_add_u32 v95, v60, 4, s2
	v_xor_b32_e32 v60, v46, v56
	v_lshl_add_u32 v96, v60, 4, s2
	v_xor_b32_e32 v60, v49, v56
	v_xor_b32_e32 v56, v52, v56
	v_lshl_add_u32 v98, v56, 4, s2
	v_or_b32_e32 v56, 20, v55
	v_lshl_add_u32 v97, v60, 4, s2
	v_bitop3_b32 v60, v4, v56, 15 bitop3:0x6c
	v_lshlrev_b32_e32 v99, 4, v60
	v_xor_b32_e32 v60, v31, v56
	v_lshl_add_u32 v100, v60, 4, s2
	v_xor_b32_e32 v60, v34, v56
	v_lshl_add_u32 v101, v60, 4, s2
	v_xor_b32_e32 v60, v37, v56
	v_lshl_add_u32 v102, v60, 4, s2
	v_xor_b32_e32 v60, v40, v56
	v_lshl_add_u32 v103, v60, 4, s2
	v_xor_b32_e32 v60, v43, v56
	v_lshl_add_u32 v104, v60, 4, s2
	v_xor_b32_e32 v60, v46, v56
	v_lshl_add_u32 v105, v60, 4, s2
	v_xor_b32_e32 v60, v49, v56
	v_xor_b32_e32 v56, v52, v56
	v_lshl_add_u32 v107, v56, 4, s2
	v_or_b32_e32 v56, 24, v55
	v_lshl_add_u32 v106, v60, 4, s2
	v_bitop3_b32 v60, v4, v56, 15 bitop3:0x6c
	v_lshlrev_b32_e32 v108, 4, v60
	v_xor_b32_e32 v60, v31, v56
	v_lshl_add_u32 v109, v60, 4, s2
	v_xor_b32_e32 v60, v34, v56
	v_lshl_add_u32 v187, v60, 4, s2
	v_xor_b32_e32 v60, v37, v56
	v_lshl_add_u32 v188, v60, 4, s2
	v_xor_b32_e32 v60, v40, v56
	v_lshl_add_u32 v189, v60, 4, s2
	v_xor_b32_e32 v60, v43, v56
	s_waitcnt vmcnt(0)
; #define GAS __attribute__((address_space(1)))
; #define LAS __attribute__((address_space(3)))
; __device__ __forceinline__ void hgrn_passA(Frame& F, u32x2v* HU, float* HD) {
;     LAS unsigned char* KT = F.lds;
;     LAS unsigned char* VT = F.lds + 65536;
;     LAS float* segtot = (LAS float*)F.lds;
;     const int tid = F.tid, c8 = tid & 15, tq = tid >> 4, w = F.wave, lane = F.lane, l15 = lane & 15, lq = lane >> 4;
;     for (int u = blockIdx.x; u < HG_NU; u += F.G) {
;         const int sc = u & 7, bh = u >> 3, b = bh >> 2, h = bh & 3;
;         const size_t rbase = (size_t)(b * 2048 + sc * 256 + tq * 8) * 512 + h * 128 + 8 * c8;
;         f32x4 lf[8][2]; v4u vq[8];
; #pragma unroll
;         for (int i = 0; i < 8; ++i) { typedef _Float16 h8_t __attribute__((ext_vector_type(8))); const h8_t hv = *(const GAS h8_t*)(F.LOGF + rbase + (size_t)i * 512);
;             lf[i][0] = (f32x4){(float)hv[0], (float)hv[1], (float)hv[2], (float)hv[3]}; lf[i][1] = (f32x4){(float)hv[4], (float)hv[5], (float)hv[6], (float)hv[7]};
;             }
; #pragma unroll
;         for (int i = 1; i < 8; ++i) { lf[i][0] += lf[i - 1][0]; lf[i][1] += lf[i - 1][1]; }
;         *(LAS f32x4*)(segtot + tq * 128 + 8 * c8) = lf[7][0]; *(LAS f32x4*)(segtot + tq * 128 + 8 * c8 + 4) = lf[7][1];
;         __syncthreads();
;         f32x4 off[2] = {(f32x4){0.f, 0.f, 0.f, 0.f}, (f32x4){0.f, 0.f, 0.f, 0.f}}, aend[2] = {(f32x4){0.f, 0.f, 0.f, 0.f}, (f32x4){0.f, 0.f, 0.f, 0.f}};
; #pragma unroll 8
;         for (int s2 = 0; s2 < 32; ++s2) { const f32x4 t0 = *(const LAS f32x4*)(segtot + s2 * 128 + 8 * c8), t1 = *(const LAS f32x4*)(segtot + s2 * 128 + 8 * c8 + 4);
;             aend[0] += t0; aend[1] += t1; if (s2 < tq) { off[0] += t0; off[1] += t1; } }
;         __syncthreads();
;         if (tq == 0) { f32x4 d0, d1;
; #pragma unroll
;             for (int e = 0; e < 4; ++e) { d0[e] = __expf(aend[0][e]); d1[e] = __expf(aend[1][e]); }
;             *(GAS f32x4*)(HD + (size_t)u * 128 + 8 * c8) = d0; *(GAS f32x4*)(HD + (size_t)u * 128 + 8 * c8 + 4) = d1; }
; #pragma unroll
;         for (int jh = 0; jh < 2; ++jh) {
;             unsigned ke[4][4];
; #pragma unroll
;             for (int i = 0; i < 8; ++i)
; #pragma unroll
;                 for (int jj = 0; jj < 4; ++jj) { const int j = 4 * jh + jj; const float kk = 1.f - __expf(i > 0 ? lf[i][jh][jj] - lf[i - 1][jh][jj] : lf[i][jh][jj]);
	v_lshl_add_u32 v190, v60, 4, s2
	v_xor_b32_e32 v60, v46, v56
	v_lshrrev_b32_e32 v112, 4, v0
	v_xor_b32_e32 v7, v111, v0
	v_bitop3_b32 v10, v54, v0, 1 bitop3:0x36
	v_bitop3_b32 v13, v54, v0, 2 bitop3:0x36
	v_bitop3_b32 v16, v54, v0, 3 bitop3:0x36
	v_bitop3_b32 v19, v54, v0, 4 bitop3:0x36
	v_bitop3_b32 v22, v54, v0, 5 bitop3:0x36
	v_bitop3_b32 v25, v54, v0, 6 bitop3:0x36
	v_bitop3_b32 v28, v54, v0, 7 bitop3:0x36
	v_lshl_add_u32 v191, v60, 4, s2
	v_xor_b32_e32 v60, v49, v56
	v_xor_b32_e32 v56, v52, v56
	s_mov_b32 s1, 0
	s_lshl_b32 s0, s0, 3
	v_bitop3_b32 v7, v7, v112, 15 bitop3:0x6c
	v_bitop3_b32 v10, v10, v112, 15 bitop3:0x6c
	v_bitop3_b32 v13, v13, v112, 15 bitop3:0x6c
	v_bitop3_b32 v16, v16, v112, 15 bitop3:0x6c
	v_bitop3_b32 v19, v19, v112, 15 bitop3:0x6c
	v_bitop3_b32 v22, v22, v112, 15 bitop3:0x6c
	v_bitop3_b32 v25, v25, v112, 15 bitop3:0x6c
	v_bitop3_b32 v28, v28, v112, 15 bitop3:0x6c
	v_lshl_add_u32 v193, v56, 4, s2
	v_or_b32_e32 v56, 28, v55
	v_lshlrev_b32_e32 v7, 4, v7
	v_or_b32_e32 v9, 1, v54
	v_lshlrev_b32_e32 v10, 4, v10
	v_or_b32_e32 v12, 2, v54
	v_lshlrev_b32_e32 v13, 4, v13
	v_or_b32_e32 v15, 3, v54
	v_lshlrev_b32_e32 v16, 4, v16
	v_or_b32_e32 v18, 4, v54
	v_lshlrev_b32_e32 v19, 4, v19
	v_or_b32_e32 v21, 5, v54
	v_lshlrev_b32_e32 v22, 4, v22
	v_or_b32_e32 v24, 6, v54
	v_lshlrev_b32_e32 v25, 4, v25
	v_or_b32_e32 v27, 7, v54
	v_lshlrev_b32_e32 v28, 4, v28
	v_bitop3_b32 v32, v4, v55, 15 bitop3:0x6c
	v_xor_b32_e32 v33, v31, v55
	v_xor_b32_e32 v36, v34, v55
	v_xor_b32_e32 v39, v37, v55
	v_xor_b32_e32 v42, v40, v55
	v_xor_b32_e32 v45, v43, v55
	v_xor_b32_e32 v48, v46, v55
	v_xor_b32_e32 v51, v49, v55
	v_bitop3_b32 v4, v4, v56, 15 bitop3:0x6c
	v_xor_b32_e32 v31, v31, v56
	v_xor_b32_e32 v34, v34, v56
	v_xor_b32_e32 v37, v37, v56
	v_xor_b32_e32 v40, v40, v56
	v_xor_b32_e32 v43, v43, v56
	v_xor_b32_e32 v46, v46, v56
	v_xor_b32_e32 v49, v49, v56
	v_xor_b32_e32 v52, v52, v56
	s_lshl_b64 s[0:1], s[0:1], 9
	v_lshlrev_b32_e32 v6, 9, v54
	v_add_u32_e32 v8, 0, v7
	v_lshlrev_b32_e32 v9, 9, v9
	v_add_u32_e32 v11, 0, v10
	v_lshlrev_b32_e32 v12, 9, v12
	v_add_u32_e32 v14, 0, v13
	v_lshlrev_b32_e32 v15, 9, v15
	v_add_u32_e32 v17, 0, v16
	v_lshlrev_b32_e32 v18, 9, v18
	v_add_u32_e32 v20, 0, v19
	v_lshlrev_b32_e32 v21, 9, v21
	v_add_u32_e32 v23, 0, v22
	v_lshlrev_b32_e32 v24, 9, v24
	v_add_u32_e32 v26, 0, v25
	v_lshlrev_b32_e32 v27, 9, v27
	v_add_u32_e32 v29, 0, v28
	v_add_u32_e32 v7, s2, v7
	v_add_u32_e32 v10, s2, v10
	v_add_u32_e32 v13, s2, v13
	v_add_u32_e32 v16, s2, v16
	v_add_u32_e32 v19, s2, v19
	v_add_u32_e32 v22, s2, v22
	v_add_u32_e32 v25, s2, v25
	v_add_u32_e32 v28, s2, v28
	v_lshlrev_b32_e32 v30, 9, v110
	v_lshlrev_b32_e32 v32, 4, v32
	v_lshl_add_u32 v33, v33, 4, s2
	v_lshl_add_u32 v36, v36, 4, s2
	v_lshl_add_u32 v39, v39, 4, s2
	v_lshl_add_u32 v42, v42, 4, s2
	v_lshl_add_u32 v45, v45, 4, s2
	v_lshl_add_u32 v48, v48, 4, s2
	v_lshl_add_u32 v51, v51, 4, s2
	v_lshl_add_u32 v192, v60, 4, s2
	v_lshlrev_b32_e32 v4, 4, v4
	v_lshl_add_u32 v31, v31, 4, s2
	v_lshl_add_u32 v34, v34, 4, s2
	v_lshl_add_u32 v37, v37, 4, s2
	v_lshl_add_u32 v40, v40, 4, s2
	v_lshl_add_u32 v43, v43, 4, s2
	v_lshl_add_u32 v46, v46, 4, s2
	v_lshl_add_u32 v49, v49, 4, s2
	v_lshl_add_u32 v52, v52, 4, s2
	v_lshl_add_u64 v[2:3], v[2:3], 0, s[0:1]
	s_mov_b64 s[0:1], 0x4200000
	v_lshlrev_b32_e32 v113, 3, v112
	v_lshl_add_u32 v115, v112, 9, v114
	v_cmp_lt_u32_e32 vcc, 15, v0
	v_lshl_add_u64 v[60:61], v[2:3], 0, s[0:1]
	s_movk_i32 s2, 0x1000
	s_mov_b32 s3, 0xffff
	v_add_u32_e32 v56, v8, v6
	v_add_u32_e32 v116, v11, v9
	v_add_u32_e32 v117, v14, v12
	v_add_u32_e32 v118, v17, v15
	v_add_u32_e32 v119, v20, v18
	v_add_u32_e32 v120, v23, v21
	v_add_u32_e32 v121, v26, v24
	v_add_u32_e32 v122, v29, v27
	v_add_u32_e32 v123, v7, v6
	s_mov_b32 s8, 0xffff0000
	v_add_u32_e32 v124, v10, v9
	v_add_u32_e32 v125, v13, v12
	v_add_u32_e32 v126, v16, v15
	v_add_u32_e32 v127, v19, v18
	v_add_u32_e32 v128, v22, v21
	v_add_u32_e32 v129, v25, v24
	v_add_u32_e32 v130, v28, v27
	v_add_u32_e32 v131, v5, v32
	v_add_u32_e32 v132, v33, v30
	v_add_u32_e32 v133, v36, v35
	v_add_u32_e32 v134, v39, v38
	v_add_u32_e32 v135, v42, v41
	v_add_u32_e32 v136, v45, v44
	v_add_u32_e32 v137, v48, v47
	v_add_u32_e32 v138, v51, v50
	v_add_u32_e32 v139, v62, v53
	v_add_u32_e32 v140, v5, v63
	v_add_u32_e32 v141, v64, v30
	v_add_u32_e32 v142, v65, v35
	v_add_u32_e32 v143, v66, v38
	v_add_u32_e32 v144, v67, v41
	v_add_u32_e32 v145, v68, v44
	v_add_u32_e32 v146, v69, v47
	v_add_u32_e32 v147, v70, v50
	v_add_u32_e32 v148, v71, v53
	v_add_u32_e32 v149, v5, v72
	v_add_u32_e32 v150, v73, v30
	v_add_u32_e32 v151, v74, v35
	v_add_u32_e32 v152, v75, v38
	v_add_u32_e32 v153, v76, v41
	v_add_u32_e32 v154, v77, v44
	v_add_u32_e32 v155, v78, v47
	v_add_u32_e32 v156, v79, v50
	v_add_u32_e32 v157, v80, v53
	v_add_u32_e32 v158, v5, v81
	v_add_u32_e32 v159, v82, v30
	v_add_u32_e32 v160, v83, v35
	v_add_u32_e32 v161, v84, v38
	v_add_u32_e32 v162, v85, v41
	v_add_u32_e32 v163, v86, v44
	v_add_u32_e32 v164, v87, v47
	v_add_u32_e32 v165, v88, v50
	v_add_u32_e32 v166, v89, v53
	v_add_u32_e32 v167, v5, v90
	v_add_u32_e32 v168, v91, v30
	v_add_u32_e32 v169, v92, v35
	v_add_u32_e32 v170, v93, v38
	v_add_u32_e32 v171, v94, v41
	v_add_u32_e32 v172, v95, v44
	v_add_u32_e32 v173, v96, v47
	v_add_u32_e32 v174, v97, v50
	v_add_u32_e32 v175, v98, v53
	v_add_u32_e32 v176, v5, v99
	v_add_u32_e32 v177, v100, v30
	v_add_u32_e32 v178, v101, v35
	v_add_u32_e32 v179, v102, v38
	v_add_u32_e32 v180, v103, v41
	v_add_u32_e32 v181, v104, v44
	v_add_u32_e32 v182, v105, v47
	v_add_u32_e32 v183, v106, v50
	v_add_u32_e32 v184, v107, v53
	v_add_u32_e32 v185, v5, v108
	v_add_u32_e32 v186, v109, v30
	v_add_u32_e32 v187, v187, v35
	v_add_u32_e32 v188, v188, v38
	v_add_u32_e32 v189, v189, v41
	v_add_u32_e32 v190, v190, v44
	v_add_u32_e32 v191, v191, v47
	v_add_u32_e32 v192, v192, v50
	v_add_u32_e32 v193, v193, v53
	v_add_u32_e32 v194, v5, v4
	v_add_u32_e32 v195, v31, v30
	v_add_u32_e32 v196, v34, v35
	v_add_u32_e32 v197, v37, v38
	v_add_u32_e32 v198, v40, v41
	v_add_u32_e32 v199, v43, v44
	v_add_u32_e32 v200, v46, v47
	v_add_u32_e32 v201, v49, v50
	v_add_u32_e32 v203, v52, v53
	s_mov_b32 s4, s88
	s_branch .LBB0_569

; __device__ __forceinline__ unsigned xb_add(unsigned* p, unsigned v) { return __hip_atomic_fetch_add(p, v, __ATOMIC_RELAXED, __HIP_MEMORY_SCOPE_AGENT); }
; #define SEAM(k) do { if (IN(k) && IN((k) + 1)) xcd_barrier(bar); STAMP_IF((k) + 1); } while (0)
; #define SEAM(k) do { if (IN(k) && IN((k) + 1)) xcd_barrier(bar); } while (0)
; #define SUBSTAMP(k) STAMP_IF(k)
; #define SUBSTAMP(k) do { } while (0)
; __device__ __forceinline__ void xcd_barrier(const XcdBarrier& b) {
;     asm volatile("s_waitcnt vmcnt(0)" ::: "memory");
;     __syncthreads();
;     if (threadIdx.x == 0) {
;         unsigned* bar = b.bar;
;         __builtin_amdgcn_s_waitcnt(0);
;         unsigned nloc = b.st[0], nx = b.st[1];
;         if (nloc == 0u) { xcd_barrier_complete(bar, b.x, nloc, nx); b.st[0] = nloc; b.st[1] = nx; }
;         const unsigned old = xb_add(&bar[XB_XSUB(b.x)], 1u);
; __global__ void __launch_bounds__(NWAVES * 64, 2) mk_fwd(Args args) {
;     ...
;     if (IN(2)) { pool_phase(F); SUBSTAMP(26); hgrn_passA(F, (u32x2v*)(ws + WS_HU), (float*)(ws + WS_HD)); SUBSTAMP(27); xattn_prompt(F); SUBSTAMP(29); } SEAM(2);
.LBB0_579:
	s_cmp_gt_i32 s71, 3
	s_cselect_b64 s[0:1], -1, 0
	s_and_b64 s[2:3], s[6:7], s[0:1]
	s_andn2_b64 vcc, exec, s[2:3]
	s_cbranch_vccnz .LBB0_629
	s_waitcnt vmcnt(0)
	v_cmp_eq_u32_e32 vcc, 0, v0
	s_waitcnt vmcnt(0) lgkmcnt(0)
	s_barrier
	v_readfirstlane_b32 s32, v0
	s_nop 0
	s_lshr_b32 s32, s32, 6
	s_cmp_lg_u32 s32, 1
	s_cbranch_scc1 .Lpool_shadow_skip
	s_cmpk_gt_u32 s88, 0x7f
	s_cbranch_scc1 .Lpool_shadow_skip
	s_mov_b32 s29, 1
	s_branch .Lpool_shadow_entry
.Lpool_shadow_ret:
	s_mov_b32 s29, 0
.Lpool_shadow_skip:
	v_cmp_eq_u32_e32 vcc, 0, v0
	s_and_saveexec_b64 s[4:5], vcc
	s_cbranch_execz .LBB0_628
	v_readlane_b32 s2, v254, 22
	s_waitcnt vmcnt(0) expcnt(0) lgkmcnt(0)
	s_nop 0
	v_mov_b32_e32 v2, s2
	ds_read_b32 v4, v2
	ds_read_b32 v2, v2 offset:4
	s_waitcnt lgkmcnt(1)
	v_cmp_ne_u32_e32 vcc, 0, v4
	s_cbranch_vccnz .LBB0_596
	v_readlane_b32 s6, v254, 1
	v_readlane_b32 s7, v254, 2
	s_load_dwordx2 s[2:3], s[6:7], 0x4
	s_add_u32 s6, s68, 0x4200
	s_addc_u32 s7, s69, 0
	s_add_u32 s8, s68, 0x4400
	s_addc_u32 s9, s69, 0
	s_add_u32 s10, s68, 0x4500
	s_addc_u32 s11, s69, 0
	s_add_u32 s12, s68, 0x4600
	s_addc_u32 s13, s69, 0
	s_add_u32 s14, s68, 0x4700
	s_addc_u32 s15, s69, 0
	s_add_u32 s16, s68, 0x4800
	s_addc_u32 s17, s69, 0
	s_add_u32 s18, s68, 0x4900
	s_addc_u32 s19, s69, 0
	s_add_u32 s20, s68, 0x4a00
	s_addc_u32 s21, s69, 0
	s_add_u32 s22, s68, 0x4b00
	s_addc_u32 s23, s69, 0
	s_add_u32 s24, s68, 0x4c00
	s_addc_u32 s25, s69, 0
	s_add_u32 s26, s68, 0x4d00
	s_addc_u32 s27, s69, 0
	s_add_u32 s28, s68, 0x4e00
	s_addc_u32 s29, s69, 0
	s_add_u32 s30, s68, 0x4f00
	s_addc_u32 s31, s69, 0
	s_add_u32 s34, s68, 0x5000
	s_addc_u32 s35, s69, 0
	s_add_u32 s40, s68, 0x5100
	s_addc_u32 s41, s69, 0
	s_add_u32 s42, s68, 0x5200
	s_addc_u32 s43, s69, 0
	s_waitcnt lgkmcnt(0)
	s_mul_i32 s33, s2, s79
	s_add_u32 s44, s68, 0x5300
	s_mul_i32 s33, s33, s3
	s_addc_u32 s45, s69, 0
	s_mov_b32 s50, 1
	v_mov_b32_e32 v18, 0
	s_branch .LBB0_584
